# pool_sample: the last four bf16 row loads (were issued one at a time behind vmcnt(0)) are issued up front with the others
# baseline (speedup 1.0000x reference)
; __device__ __forceinline__ int tid_opaque() { int t = threadIdx.x; asm volatile("" : "+v"(t)); return t; }
; __device__ __forceinline__ float bf2f(unsigned b) { return __uint_as_float(b << 16); }
; __device__ __forceinline__ void pool_sample(const Params& p, int s, int g) {
;     const int col = g * 512 + tid_opaque(), w = 2 << g;
;     const bf16_t* PROJ = (const bf16_t*)(p.ws + W_PROJ);
;     bf16_t* POOLED = (bf16_t*)(p.ws + W_XN);
;     float v[23];
; #pragma unroll
;     for (int j = 0; j < 15; ++j) v[j] = __builtin_nontemporal_load(p.state_pool + ((size_t)s * 15 + j) * DM + col);
; #pragma unroll
;     for (int t = 0; t < 8; ++t) v[15 + t] = bf2f(PROJ[(size_t)(ROWS_P + s * 8 + t) * NPROJ + C_U + col]);
;     const float inv = 1.0f / (float)w;
.LBB0_412:
	s_and_b32 s47, s46, 3
	s_cmpk_gt_i32 s46, 0x21f
	s_mov_b64 s[2:3], -1
	s_cbranch_scc0 .LBB0_414
	v_mov_b32_e32 v0, v192
	s_add_i32 s2, s46, 0xfffffde0
	s_lshr_b32 s2, s2, 2
	v_lshl_add_u32 v4, s47, 9, v0
	v_ashrrev_i32_e32 v5, 31, v4
	v_readlane_b32 s48, v244, 12
	v_lshlrev_b64 v[2:3], 2, v[4:5]
	v_readlane_b32 s56, v244, 20
	v_readlane_b32 s57, v244, 21
	s_mul_i32 s6, s2, 0x7800
	s_lshl_b64 s[10:11], s[6:7], 2
	v_lshl_add_u64 v[6:7], s[56:57], 0, v[2:3]
	s_waitcnt vmcnt(7)
	v_lshl_add_u64 v[14:15], v[6:7], 0, s[10:11]
	v_add_co_u32_e32 v6, vcc, 0x2000, v14
	global_load_dword v17, v[14:15], off nt
	s_nop 0
	v_addc_co_u32_e32 v7, vcc, 0, v15, vcc
	global_load_dword v20, v[6:7], off nt
	v_add_co_u32_e32 v6, vcc, 0x4000, v14
	s_lshl_b32 s3, s2, 3
	s_nop 0
	v_addc_co_u32_e32 v7, vcc, 0, v15, vcc
	global_load_dword v21, v[6:7], off nt
	v_add_co_u32_e32 v6, vcc, 0x6000, v14
	s_addk_i32 s3, 0x2200
	s_nop 0
	v_addc_co_u32_e32 v7, vcc, 0, v15, vcc
	global_load_dword v22, v[6:7], off nt
	v_add_co_u32_e32 v6, vcc, 0x8000, v14
	s_mul_i32 s6, s3, 0x3500
	s_nop 0
	v_addc_co_u32_e32 v7, vcc, 0, v15, vcc
	global_load_dword v23, v[6:7], off nt
	v_add_co_u32_e32 v6, vcc, 0xa000, v14
	s_lshl_b64 s[4:5], s[6:7], 1
	s_nop 0
	v_addc_co_u32_e32 v7, vcc, 0, v15, vcc
	global_load_dword v24, v[6:7], off nt
	v_add_co_u32_e32 v6, vcc, 0xc000, v14
	s_add_u32 s4, s88, s4
	s_nop 0
	v_addc_co_u32_e32 v7, vcc, 0, v15, vcc
	global_load_dword v25, v[6:7], off nt
	v_add_co_u32_e32 v6, vcc, 0xe000, v14
	s_addc_u32 s5, s89, s5
	s_nop 0
	v_addc_co_u32_e32 v7, vcc, 0, v15, vcc
	global_load_dword v26, v[6:7], off nt
	v_add_co_u32_e32 v6, vcc, 0x10000, v14
	v_lshlrev_b64 v[4:5], 1, v[4:5]
	s_nop 0
	v_addc_co_u32_e32 v7, vcc, 0, v15, vcc
	global_load_dword v0, v[6:7], off nt
	v_add_co_u32_e32 v6, vcc, 0x12000, v14
	v_readlane_b32 s49, v244, 13
	s_nop 0
	v_addc_co_u32_e32 v7, vcc, 0, v15, vcc
	v_add_co_u32_e32 v8, vcc, 0x14000, v14
	global_load_dword v6, v[6:7], off nt
	s_nop 0
	v_addc_co_u32_e32 v9, vcc, 0, v15, vcc
	global_load_dword v7, v[8:9], off nt
	v_add_co_u32_e32 v8, vcc, 0x16000, v14
	v_readlane_b32 s50, v244, 14
	s_nop 0
	v_addc_co_u32_e32 v9, vcc, 0, v15, vcc
	v_add_co_u32_e32 v12, vcc, 0x18000, v14
	global_load_dword v8, v[8:9], off nt
	s_nop 0
	v_addc_co_u32_e32 v13, vcc, 0, v15, vcc
	global_load_dword v9, v[12:13], off nt
	v_add_co_u32_e32 v12, vcc, 0x1a000, v14
	v_readlane_b32 s51, v244, 15
	s_nop 0
	v_addc_co_u32_e32 v13, vcc, 0, v15, vcc
	v_add_co_u32_e32 v14, vcc, 0x1c000, v14
	global_load_dword v12, v[12:13], off nt
	s_nop 0
	v_addc_co_u32_e32 v15, vcc, 0, v15, vcc
	global_load_dword v13, v[14:15], off nt
	v_lshl_add_u64 v[14:15], s[4:5], 0, v[4:5]
	s_add_i32 s4, s6, 0x3500
	s_mov_b32 s5, s7
	s_lshl_b64 s[4:5], s[4:5], 1
	s_add_u32 s4, s88, s4
	s_addc_u32 s5, s89, s5
	v_add_co_u32_e32 v14, vcc, s24, v14
	s_waitcnt vmcnt(21)
	v_lshl_add_u64 v[18:19], s[4:5], 0, v[4:5]
	s_add_i32 s4, s6, 0x6a00
	s_mov_b32 s5, s7
	v_addc_co_u32_e32 v15, vcc, 0, v15, vcc
	s_lshl_b64 s[4:5], s[4:5], 1
	v_add_co_u32_e32 v18, vcc, s24, v18
	s_add_u32 s4, s88, s4
	s_nop 0
	v_addc_co_u32_e32 v19, vcc, 0, v19, vcc
	s_addc_u32 s5, s89, s5
	s_mov_b32 s13, 0
	s_mov_b32 s12, 0x1a800
	v_lshl_add_u64 v[246:247], v[14:15], 0, s[12:13]
	s_mov_b32 s12, 0x21200
	v_lshl_add_u64 v[248:249], v[14:15], 0, s[12:13]
	s_mov_b32 s12, 0x27c00
	v_lshl_add_u64 v[250:251], v[14:15], 0, s[12:13]
	s_mov_b32 s12, 0x2e600
	v_lshl_add_u64 v[252:253], v[14:15], 0, s[12:13]
	global_load_ushort v246, v[246:247], off offset:2048
	global_load_ushort v248, v[248:249], off offset:2048
	global_load_ushort v250, v[250:251], off offset:2048
	global_load_ushort v252, v[252:253], off offset:2048
	global_load_ushort v14, v[14:15], off offset:2048
	v_readlane_b32 s52, v244, 16
	global_load_ushort v15, v[18:19], off offset:2048
	v_lshl_add_u64 v[18:19], s[4:5], 0, v[4:5]
	s_add_i32 s4, s6, 0x9f00
	s_mov_b32 s5, s7
	s_lshl_b64 s[4:5], s[4:5], 1
	v_add_co_u32_e32 v18, vcc, s24, v18
	s_add_u32 s4, s88, s4
	s_nop 0
	v_addc_co_u32_e32 v19, vcc, 0, v19, vcc
	s_addc_u32 s5, s89, s5
	global_load_ushort v16, v[18:19], off offset:2048
	v_lshl_add_u64 v[18:19], s[4:5], 0, v[4:5]
	v_add_co_u32_e32 v18, vcc, s24, v18
	s_add_i32 s4, s6, 0xd400
	s_nop 0
	v_addc_co_u32_e32 v19, vcc, 0, v19, vcc
	global_load_ushort v18, v[18:19], off offset:2048
	s_mov_b32 s5, s7
	s_lshl_b64 s[4:5], s[4:5], 1
	s_add_u32 s4, s88, s4
	s_addc_u32 s5, s89, s5
	v_readlane_b32 s53, v244, 17
	v_readlane_b32 s54, v244, 18
	v_readlane_b32 s55, v244, 19
	v_readlane_b32 s58, v244, 22
	v_readlane_b32 s59, v244, 23
	v_readlane_b32 s60, v244, 24
	v_readlane_b32 s61, v244, 25
	v_readlane_b32 s62, v244, 26
	v_readlane_b32 s63, v244, 27
	s_waitcnt vmcnt(3)
	v_lshlrev_b32_e32 v14, 16, v14
	s_waitcnt vmcnt(2)
	v_lshlrev_b32_e32 v15, 16, v15
	s_waitcnt vmcnt(1)
	v_lshlrev_b32_e32 v16, 16, v16
	s_waitcnt vmcnt(0)
	v_lshlrev_b32_e32 v27, 16, v18
	v_lshl_add_u64 v[18:19], s[4:5], 0, v[4:5]
	v_add_co_u32_e32 v18, vcc, s24, v18
	s_add_i32 s4, s6, 0x10900
	s_nop 0
	v_addc_co_u32_e32 v19, vcc, 0, v19, vcc
	v_mov_b32_e32 v18, v246
	s_mov_b32 s5, s7
	s_lshl_b64 s[4:5], s[4:5], 1
	s_add_u32 s4, s88, s4
	s_addc_u32 s5, s89, s5
	s_waitcnt vmcnt(0)
	v_lshlrev_b32_e32 v28, 16, v18
	v_lshl_add_u64 v[18:19], s[4:5], 0, v[4:5]
	v_add_co_u32_e32 v18, vcc, s24, v18
	s_add_i32 s4, s6, 0x13e00
	s_nop 0
	v_addc_co_u32_e32 v19, vcc, 0, v19, vcc
	v_mov_b32_e32 v18, v248
	s_mov_b32 s5, s7
	s_lshl_b64 s[4:5], s[4:5], 1
	s_add_u32 s4, s88, s4
	s_addc_u32 s5, s89, s5
	s_add_i32 s6, s6, 0x17300
	s_lshl_b32 s2, s2, 14
	s_waitcnt vmcnt(0)
; __device__ __forceinline__ float bf2f(unsigned b) { return __uint_as_float(b << 16); }
; __device__ __forceinline__ bf16_t f2bf(float f) { return (bf16_t)(pk2(f, 0.f) & 0xffffu); }
; __device__ __forceinline__ void pool_sample(const Params& p, int s, int g) {
;     ...
;     for (int t = 0; t < 8; ++t) v[15 + t] = bf2f(PROJ[(size_t)(ROWS_P + s * 8 + t) * NPROJ + C_U + col]);
;     const float inv = 1.0f / (float)w;
; #pragma unroll
;     for (int t = 0; t < 8; ++t) { float sum = 0.f;
; #pragma unroll
;         for (int k = 0; k < 16; ++k) sum += (k < w) ? v[15 + t - k] : 0.f;
;         POOLED[(size_t)(ROWS_P + s * 8 + t) * DM + col] = f2bf(sum * inv - v[15 + t]); }
	v_lshlrev_b32_e32 v29, 16, v18
	v_lshl_add_u64 v[18:19], s[4:5], 0, v[4:5]
	v_add_co_u32_e32 v18, vcc, s24, v18
	s_lshl_b64 s[4:5], s[6:7], 1
	s_nop 0
	v_addc_co_u32_e32 v19, vcc, 0, v19, vcc
	v_mov_b32_e32 v18, v250
	s_add_u32 s4, s88, s4
	s_addc_u32 s5, s89, s5
	s_waitcnt vmcnt(0)
	v_lshlrev_b32_e32 v30, 16, v18
	v_lshl_add_u64 v[18:19], s[4:5], 0, v[4:5]
	v_add_co_u32_e32 v18, vcc, s24, v18
	s_lshl_b32 s4, s47, 23
	s_nop 0
	v_addc_co_u32_e32 v19, vcc, 0, v19, vcc
	v_mov_b32_e32 v18, v252
	s_add_i32 s4, s4, 0x800000
	s_xor_b32 s48, s4, 1.0
	s_cmp_eq_u32 s47, 0
	s_cselect_b64 s[12:13], -1, 0
	v_cndmask_b32_e64 v32, v12, 0, s[12:13]
	s_cmp_gt_u32 s47, 1
	v_cndmask_b32_e64 v19, v9, 0, s[12:13]
	s_cselect_b64 vcc, -1, 0
	v_cndmask_b32_e32 v33, 0, v8, vcc
	v_cndmask_b32_e32 v34, 0, v7, vcc
	v_cndmask_b32_e32 v35, 0, v6, vcc
	s_cmp_eq_u32 s47, 3
	s_cselect_b64 s[4:5], -1, 0
	v_cndmask_b32_e64 v26, 0, v26, s[4:5]
	v_cndmask_b32_e64 v25, 0, v25, s[4:5]
	v_cndmask_b32_e64 v24, 0, v24, s[4:5]
	v_cndmask_b32_e64 v23, 0, v23, s[4:5]
	v_cndmask_b32_e64 v22, 0, v22, s[4:5]
	v_cndmask_b32_e64 v21, 0, v21, s[4:5]
	v_cndmask_b32_e64 v20, 0, v20, s[4:5]
	v_cndmask_b32_e64 v17, 0, v17, s[4:5]
	v_lshl_add_u64 v[4:5], s[88:89], 0, v[4:5]
	s_lshl_b32 s6, s3, 12
	v_cndmask_b32_e64 v36, v13, 0, s[12:13]
	s_waitcnt vmcnt(0)
	v_lshlrev_b32_e32 v31, 16, v18
	v_add_f32_e32 v18, 0, v14
	v_add_f32_e32 v18, v13, v18
	v_add_f32_e32 v18, v32, v18
	v_add_f32_e32 v18, v19, v18
	v_add_f32_e32 v18, v33, v18
	v_add_f32_e32 v18, v34, v18
	v_add_f32_e32 v18, v35, v18
	v_cndmask_b32_e32 v19, 0, v0, vcc
	v_add_f32_e32 v18, v19, v18
	v_add_f32_e32 v18, v26, v18
	v_add_f32_e32 v18, v25, v18
	v_add_f32_e32 v18, v24, v18
	v_add_f32_e32 v18, v23, v18
	v_add_f32_e32 v18, v22, v18
	v_add_f32_e32 v18, v21, v18
	v_add_f32_e32 v18, v20, v18
	v_add_f32_e32 v17, v17, v18
	v_fma_f32 v17, s48, v17, -v14
	v_cvt_pk_bf16_f32 v17, v17, v1
	v_lshl_add_u64 v[18:19], v[4:5], 0, s[6:7]
	global_store_short v[18:19], v17, off
	v_add_f32_e32 v17, 0, v15
	v_add_f32_e32 v17, v17, v14
	v_add_f32_e32 v17, v36, v17
	v_add_f32_e32 v17, v32, v17
	v_cndmask_b32_e32 v32, 0, v9, vcc
	v_add_f32_e32 v17, v32, v17
	v_add_f32_e32 v17, v33, v17
	v_add_f32_e32 v17, v34, v17
	v_add_f32_e32 v17, v35, v17
	v_cndmask_b32_e64 v35, 0, v0, s[4:5]
	v_add_f32_e32 v17, v35, v17
	v_add_f32_e32 v17, v26, v17
	v_add_f32_e32 v17, v25, v17
	v_add_f32_e32 v17, v24, v17
	v_add_f32_e32 v17, v23, v17
	v_add_f32_e32 v17, v22, v17
	v_add_f32_e32 v17, v21, v17
	v_add_f32_e32 v17, v20, v17
	v_fma_f32 v17, s48, v17, -v15
	s_add_i32 s6, s2, 0x1100800
	v_cvt_pk_bf16_f32 v17, v17, v1
	v_lshl_add_u64 v[18:19], s[6:7], 1, v[4:5]
	global_store_short v[18:19], v17, off
	v_add_f32_e32 v17, 0, v16
	v_add_f32_e32 v17, v17, v15
	v_cndmask_b32_e64 v20, v14, 0, s[12:13]
	v_add_f32_e32 v17, v20, v17
	v_add_f32_e32 v17, v36, v17
	v_cndmask_b32_e32 v36, 0, v12, vcc
	v_add_f32_e32 v17, v36, v17
	v_add_f32_e32 v17, v32, v17
	v_add_f32_e32 v17, v33, v17
	v_add_f32_e32 v17, v34, v17
	v_cndmask_b32_e64 v34, 0, v6, s[4:5]
	v_add_f32_e32 v17, v34, v17
	v_add_f32_e32 v17, v35, v17
	v_add_f32_e32 v17, v26, v17
	v_add_f32_e32 v17, v25, v17
	v_add_f32_e32 v17, v24, v17
	v_add_f32_e32 v17, v23, v17
	v_add_f32_e32 v17, v22, v17
	v_add_f32_e32 v17, v21, v17
	v_fma_f32 v17, s48, v17, -v16
	s_add_i32 s6, s2, 0x1101000
	v_cvt_pk_bf16_f32 v17, v17, v1
	v_lshl_add_u64 v[18:19], s[6:7], 1, v[4:5]
	global_store_short v[18:19], v17, off
	v_add_f32_e32 v17, 0, v27
	v_add_f32_e32 v17, v17, v16
	v_cndmask_b32_e64 v21, v15, 0, s[12:13]
	v_add_f32_e32 v17, v21, v17
	v_add_f32_e32 v17, v20, v17
	v_cndmask_b32_e32 v20, 0, v13, vcc
	v_add_f32_e32 v17, v20, v17
	v_add_f32_e32 v17, v36, v17
	v_add_f32_e32 v17, v32, v17
	v_add_f32_e32 v17, v33, v17
	v_cndmask_b32_e64 v33, 0, v7, s[4:5]
	v_add_f32_e32 v17, v33, v17
	v_add_f32_e32 v17, v34, v17
	v_add_f32_e32 v17, v35, v17
	v_add_f32_e32 v17, v26, v17
	v_add_f32_e32 v17, v25, v17
	v_add_f32_e32 v17, v24, v17
	v_add_f32_e32 v17, v23, v17
	v_add_f32_e32 v17, v22, v17
	v_fma_f32 v17, s48, v17, -v27
	s_add_i32 s6, s2, 0x1101800
	v_cvt_pk_bf16_f32 v17, v17, v1
	v_lshl_add_u64 v[18:19], s[6:7], 1, v[4:5]
	global_store_short v[18:19], v17, off
	v_add_f32_e32 v17, 0, v28
	v_add_f32_e32 v17, v17, v27
	v_cndmask_b32_e64 v22, v16, 0, s[12:13]
	v_add_f32_e32 v17, v22, v17
	v_add_f32_e32 v17, v21, v17
	v_cndmask_b32_e32 v21, 0, v14, vcc
	v_add_f32_e32 v17, v21, v17
	v_add_f32_e32 v17, v20, v17
	v_add_f32_e32 v17, v36, v17
	v_add_f32_e32 v17, v32, v17
	v_cndmask_b32_e64 v32, 0, v8, s[4:5]
	v_add_f32_e32 v17, v32, v17
; __device__ __forceinline__ bf16_t f2bf(float f) { return (bf16_t)(pk2(f, 0.f) & 0xffffu); }
; __device__ __forceinline__ void pool_sample(const Params& p, int s, int g) {
;     ...
; #pragma unroll
;     for (int t = 0; t < 8; ++t) { float sum = 0.f;
; #pragma unroll
;         for (int k = 0; k < 16; ++k) sum += (k < w) ? v[15 + t - k] : 0.f;
;         POOLED[(size_t)(ROWS_P + s * 8 + t) * DM + col] = f2bf(sum * inv - v[15 + t]); }
; #pragma unroll
;     for (int j = 0; j < 15; ++j) p.out[O_PS + ((size_t)s * 15 + j) * DM + col] = v[j + 8];
	v_add_f32_e32 v17, v33, v17
	v_add_f32_e32 v17, v34, v17
	v_add_f32_e32 v17, v35, v17
	v_add_f32_e32 v17, v26, v17
	v_add_f32_e32 v17, v25, v17
	v_add_f32_e32 v17, v24, v17
	v_add_f32_e32 v17, v23, v17
	v_fma_f32 v17, s48, v17, -v28
	s_add_i32 s6, s2, 0x1102000
	v_cvt_pk_bf16_f32 v17, v17, v1
	v_lshl_add_u64 v[18:19], s[6:7], 1, v[4:5]
	global_store_short v[18:19], v17, off
	v_add_f32_e32 v17, 0, v29
	v_add_f32_e32 v17, v17, v28
	v_cndmask_b32_e64 v23, v27, 0, s[12:13]
	v_add_f32_e32 v17, v23, v17
	v_add_f32_e32 v17, v22, v17
	v_cndmask_b32_e32 v22, 0, v15, vcc
	v_add_f32_e32 v17, v22, v17
	v_add_f32_e32 v17, v21, v17
	v_add_f32_e32 v17, v20, v17
	v_add_f32_e32 v17, v36, v17
	v_cndmask_b32_e64 v36, 0, v9, s[4:5]
	v_add_f32_e32 v17, v36, v17
	v_add_f32_e32 v17, v32, v17
	v_add_f32_e32 v17, v33, v17
	v_add_f32_e32 v17, v34, v17
	v_add_f32_e32 v17, v35, v17
	v_add_f32_e32 v17, v26, v17
	v_add_f32_e32 v17, v25, v17
	v_add_f32_e32 v17, v24, v17
	v_fma_f32 v17, s48, v17, -v29
	s_add_i32 s6, s2, 0x1102800
	v_cvt_pk_bf16_f32 v17, v17, v1
	v_lshl_add_u64 v[18:19], s[6:7], 1, v[4:5]
	global_store_short v[18:19], v17, off
	v_add_f32_e32 v17, 0, v30
	v_add_f32_e32 v17, v17, v29
	v_cndmask_b32_e64 v24, v28, 0, s[12:13]
	v_add_f32_e32 v17, v24, v17
	v_add_f32_e32 v17, v23, v17
	v_cndmask_b32_e32 v23, 0, v16, vcc
	v_add_f32_e32 v17, v23, v17
	v_add_f32_e32 v17, v22, v17
	v_add_f32_e32 v17, v21, v17
	v_add_f32_e32 v17, v20, v17
	v_cndmask_b32_e64 v20, 0, v12, s[4:5]
	v_add_f32_e32 v17, v20, v17
	v_add_f32_e32 v17, v36, v17
	v_add_f32_e32 v17, v32, v17
	v_add_f32_e32 v17, v33, v17
	v_add_f32_e32 v17, v34, v17
	v_add_f32_e32 v17, v35, v17
	v_add_f32_e32 v17, v26, v17
	v_add_f32_e32 v17, v25, v17
	v_fma_f32 v17, s48, v17, -v30
	s_add_i32 s6, s2, 0x1103000
	v_cvt_pk_bf16_f32 v17, v17, v1
	v_lshl_add_u64 v[18:19], s[6:7], 1, v[4:5]
	global_store_short v[18:19], v17, off
	v_add_f32_e32 v17, 0, v31
	v_add_f32_e32 v17, v17, v30
	v_cndmask_b32_e64 v18, v29, 0, s[12:13]
	v_add_f32_e32 v17, v18, v17
	v_add_f32_e32 v17, v24, v17
	v_cndmask_b32_e32 v18, 0, v27, vcc
	v_add_f32_e32 v17, v18, v17
	v_add_f32_e32 v17, v23, v17
	v_add_f32_e32 v17, v22, v17
	v_add_f32_e32 v17, v21, v17
	v_cndmask_b32_e64 v18, 0, v13, s[4:5]
	v_add_f32_e32 v17, v18, v17
	v_add_f32_e32 v17, v20, v17
	v_add_f32_e32 v17, v36, v17
	v_add_f32_e32 v17, v32, v17
	v_add_f32_e32 v17, v33, v17
	v_add_f32_e32 v17, v34, v17
	s_add_i32 s6, s2, 0x1103800
	v_add_f32_e32 v17, v35, v17
	s_add_u32 s2, s86, s10
	v_add_f32_e32 v17, v26, v17
	s_addc_u32 s3, s87, s11
	v_fma_f32 v17, s48, v17, -v31
	v_lshl_add_u64 v[4:5], s[6:7], 1, v[4:5]
	v_lshl_add_u64 v[2:3], s[2:3], 0, v[2:3]
	v_cvt_pk_bf16_f32 v17, v17, v1
	global_store_short v[4:5], v17, off
	v_add_co_u32_e32 v4, vcc, s26, v2
	s_nop 1
	v_addc_co_u32_e32 v5, vcc, 0, v3, vcc
	global_store_dword v[4:5], v0, off
	v_add_co_u32_e32 v4, vcc, s27, v2
	s_nop 1
	v_addc_co_u32_e32 v5, vcc, 0, v3, vcc
	global_store_dword v[4:5], v6, off
	v_add_co_u32_e32 v4, vcc, s28, v2
	s_nop 1
	v_addc_co_u32_e32 v5, vcc, 0, v3, vcc
	global_store_dword v[4:5], v7, off
	v_add_co_u32_e32 v4, vcc, s29, v2
	s_nop 1
	v_addc_co_u32_e32 v5, vcc, 0, v3, vcc
	global_store_dword v[4:5], v8, off
	v_add_co_u32_e32 v4, vcc, s30, v2
	s_nop 1
	v_addc_co_u32_e32 v5, vcc, 0, v3, vcc
	global_store_dword v[4:5], v9, off
	v_add_co_u32_e32 v4, vcc, s31, v2
	s_nop 1
	v_addc_co_u32_e32 v5, vcc, 0, v3, vcc
	global_store_dword v[4:5], v12, off
	v_add_co_u32_e32 v4, vcc, s33, v2
	s_nop 1
	v_addc_co_u32_e32 v5, vcc, 0, v3, vcc
	global_store_dword v[4:5], v13, off
	v_add_co_u32_e32 v4, vcc, s34, v2
	s_nop 1
	v_addc_co_u32_e32 v5, vcc, 0, v3, vcc
	global_store_dword v[4:5], v14, off
	v_add_co_u32_e32 v4, vcc, s35, v2
	s_nop 1
	v_addc_co_u32_e32 v5, vcc, 0, v3, vcc
	global_store_dword v[4:5], v15, off
	v_add_co_u32_e32 v4, vcc, s36, v2
	s_nop 1
	v_addc_co_u32_e32 v5, vcc, 0, v3, vcc
	global_store_dword v[4:5], v16, off
	v_add_co_u32_e32 v4, vcc, s37, v2
	s_nop 1
	v_addc_co_u32_e32 v5, vcc, 0, v3, vcc
	global_store_dword v[4:5], v27, off
	v_add_co_u32_e32 v4, vcc, s38, v2
	s_nop 1
	v_addc_co_u32_e32 v5, vcc, 0, v3, vcc
	global_store_dword v[4:5], v28, off
	v_add_co_u32_e32 v4, vcc, 0xd134000, v2
	s_nop 1
	v_addc_co_u32_e32 v5, vcc, 0, v3, vcc
	global_store_dword v[4:5], v29, off
	v_add_co_u32_e32 v4, vcc, 0xd136000, v2
	s_nop 1
	v_addc_co_u32_e32 v5, vcc, 0, v3, vcc
	v_add_co_u32_e32 v2, vcc, 0xd138000, v2
	global_store_dword v[4:5], v30, off
	s_nop 0
	v_addc_co_u32_e32 v3, vcc, 0, v3, vcc
	global_store_dword v[2:3], v31, off
	s_cbranch_execnz .LBB0_411
	s_branch .LBB0_415
